# v30: v29 plus attention QK MFMA chains start from SrcC=0 (16 zero-init moves per tile removed)
# speedup vs baseline: 1.0252x; 1.0041x over previous
.LBB0_2414:
	s_nop 1
	ds_read_b128 v[188:191], v181 offset:12288
	ds_read_b128 v[196:199], v181 offset:18432
	ds_read_b128 v[192:195], v182 offset:12288
	ds_read_b128 v[200:203], v182 offset:18432
	v_add_f32_e32 v2, 0, v150
	v_add_f32_e32 v2, v151, v2
	v_add_f32_e32 v2, v152, v2
	v_add_f32_e32 v2, v153, v2
	s_waitcnt lgkmcnt(1)
	v_mfma_scale_f32_32x32x64_f8f6f4 v[84:99], v[188:195], v[116:123], 0, v170, v170 op_sel_hi:[0,0,0]
	s_waitcnt lgkmcnt(0)
	v_mfma_scale_f32_32x32x64_f8f6f4 v[68:83], v[196:203], v[116:123], 0, v170, v170 op_sel_hi:[0,0,0]
	ds_read_b128 v[188:191], v181 offset:12352
	ds_read_b128 v[196:199], v181 offset:18496
	ds_read_b128 v[192:195], v182 offset:12352
	ds_read_b128 v[200:203], v182 offset:18496
	v_add_f32_e32 v2, v154, v2
	v_add_f32_e32 v2, v165, v2
	v_add_f32_e32 v2, v166, v2
	v_add_f32_e32 v2, v168, v2
	v_add_f32_e32 v2, v145, v2
	s_waitcnt lgkmcnt(1)
	v_mfma_scale_f32_32x32x64_f8f6f4 v[84:99], v[188:195], v[108:115], v[84:99], v170, v170 op_sel_hi:[0,0,0]
	s_waitcnt lgkmcnt(0)
	v_mfma_scale_f32_32x32x64_f8f6f4 v[68:83], v[196:203], v[108:115], v[68:83], v170, v170 op_sel_hi:[0,0,0]
	ds_read_b128 v[188:191], v181 offset:12416
	ds_read_b128 v[196:199], v181 offset:18560
	ds_read_b128 v[192:195], v182 offset:12416
	ds_read_b128 v[200:203], v182 offset:18560
	v_add_f32_e32 v2, v146, v2
	v_add_f32_e32 v2, v147, v2
	v_add_f32_e32 v2, v148, v2
	v_exp_f32_e32 v169, v140
	v_add_f32_e32 v2, v149, v2
	s_waitcnt lgkmcnt(1)
	v_mfma_scale_f32_32x32x64_f8f6f4 v[84:99], v[188:195], v[100:107], v[84:99], v170, v170 op_sel_hi:[0,0,0]
	v_exp_f32_e32 v188, v141
	v_add_f32_e32 v2, v155, v2
	v_exp_f32_e32 v136, v136
	v_add_f32_e32 v2, v164, v2
	v_exp_f32_e32 v137, v137
	v_add_f32_e32 v2, v167, v2
	v_exp_f32_e32 v134, v134
	v_add_f32_e32 v2, v169, v2
	v_exp_f32_e32 v135, v135
	v_add_f32_e32 v2, v188, v2
	v_exp_f32_e32 v130, v130
	v_add_f32_e32 v2, v136, v2
	v_exp_f32_e32 v131, v131
	v_add_f32_e32 v2, v137, v2
	v_exp_f32_e32 v128, v128
	v_add_f32_e32 v2, v134, v2
	v_exp_f32_e32 v129, v129
	v_add_f32_e32 v2, v135, v2
	v_exp_f32_e32 v189, v142
	v_add_f32_e32 v2, v130, v2
	v_exp_f32_e32 v190, v143
	v_add_f32_e32 v2, v131, v2
	v_exp_f32_e32 v138, v138
	v_add_f32_e32 v2, v128, v2
	v_exp_f32_e32 v139, v139
	v_add_f32_e32 v2, v129, v2
	v_exp_f32_e32 v132, v132
	v_add_f32_e32 v2, v189, v2
	v_exp_f32_e32 v133, v133
	v_add_f32_e32 v2, v190, v2
	v_add_f32_e32 v2, v138, v2
	v_add_f32_e32 v2, v139, v2
	v_add_f32_e32 v2, v132, v2
	v_add_f32_e32 v2, v133, v2
	v_mov_b32_e32 v187, v2
	v_cvt_pk_bf16_f32 v140, v150, v151
	v_cvt_pk_bf16_f32 v141, v152, v153
	v_cvt_pk_bf16_f32 v142, v154, v165
	v_cvt_pk_bf16_f32 v143, v166, v168
	v_cvt_pk_bf16_f32 v144, v145, v146
	v_cvt_pk_bf16_f32 v145, v147, v148
	v_cvt_pk_bf16_f32 v146, v149, v155
	v_cvt_pk_bf16_f32 v147, v164, v167
	v_cvt_pk_bf16_f32 v148, v169, v188
	v_cvt_pk_bf16_f32 v149, v136, v137
	v_cvt_pk_bf16_f32 v150, v134, v135
	v_cvt_pk_bf16_f32 v151, v130, v131
	v_cvt_pk_bf16_f32 v152, v128, v129
	v_cvt_pk_bf16_f32 v153, v189, v190
	v_cvt_pk_bf16_f32 v154, v138, v139
	v_cvt_pk_bf16_f32 v155, v132, v133
	s_waitcnt lgkmcnt(0)
	v_mfma_scale_f32_32x32x64_f8f6f4 v[68:83], v[196:203], v[100:107], v[68:83], v170, v170 op_sel_hi:[0,0,0]
	v_permlane32_swap_b32_e32 v2, v187
	v_permlane32_swap_b32_e32 v140, v142
	v_permlane32_swap_b32_e32 v141, v143
	v_permlane32_swap_b32_e32 v144, v146
	v_permlane32_swap_b32_e32 v145, v147
	v_permlane32_swap_b32_e32 v148, v150
	v_permlane32_swap_b32_e32 v149, v151
	v_permlane32_swap_b32_e32 v152, v154
	v_permlane32_swap_b32_e32 v153, v155
	s_nop 15
	s_nop 15
	v_lshl_add_u64 v[166:167], s[38:39], 0, v[162:163]
	s_mov_b32 s0, 0x2a108000
	v_add_co_u32_e32 v128, vcc, s0, v166
	v_lshl_add_u64 v[168:169], s[38:39], 0, v[160:161]
	s_nop 0
	v_addc_co_u32_e32 v129, vcc, 0, v167, vcc
	v_add_co_u32_e32 v132, vcc, 0x2a10a000, v166
	v_lshl_add_u64 v[164:165], s[38:39], 0, v[158:159]
	s_nop 0
	v_addc_co_u32_e32 v133, vcc, 0, v167, vcc
	v_add_co_u32_e32 v136, vcc, 0x1e106000, v168
	global_load_dwordx4 v[128:131], v[128:129], off
	s_nop 0
	global_load_dwordx4 v[132:135], v[132:133], off
	v_addc_co_u32_e32 v137, vcc, 0, v169, vcc
	global_load_dwordx4 v[136:139], v[136:137], off
	s_and_saveexec_b64 s[14:15], s[12:13]
	s_cbranch_execz .LBB0_2416
	v_add_co_u32_e32 v124, vcc, 0x1e106000, v164
	s_nop 1
	v_addc_co_u32_e32 v125, vcc, 0, v165, vcc
	global_load_dwordx4 v[124:127], v[124:125], off

.LBB0_2422:
	v_cndmask_b32_e64 v185, v128, v185, s[14:15]
	v_mul_f32_e32 v138, 0xbdd53b94, v185
	v_fmamk_f32 v84, v84, 0x3dd53b94, v138
	v_fmamk_f32 v85, v85, 0x3dd53b94, v138
	v_fmamk_f32 v86, v86, 0x3dd53b94, v138
	v_fmamk_f32 v87, v87, 0x3dd53b94, v138
	v_fmamk_f32 v88, v88, 0x3dd53b94, v138
	v_fmamk_f32 v89, v89, 0x3dd53b94, v138
	v_fmamk_f32 v90, v90, 0x3dd53b94, v138
	v_fmamk_f32 v91, v91, 0x3dd53b94, v138
	v_fmamk_f32 v92, v92, 0x3dd53b94, v138
	v_fmamk_f32 v93, v93, 0x3dd53b94, v138
	v_fmamk_f32 v94, v94, 0x3dd53b94, v138
	v_fmamk_f32 v95, v95, 0x3dd53b94, v138
	v_fmamk_f32 v96, v96, 0x3dd53b94, v138
	v_fmamk_f32 v97, v97, 0x3dd53b94, v138
	v_fmamk_f32 v98, v98, 0x3dd53b94, v138
	v_fmamk_f32 v99, v99, 0x3dd53b94, v138
	v_exp_f32_e32 v131, v84
	v_exp_f32_e32 v134, v85
	v_exp_f32_e32 v135, v86
	v_exp_f32_e32 v139, v87
	v_exp_f32_e32 v142, v88
	v_exp_f32_e32 v143, v89
	v_exp_f32_e32 v144, v90
	v_exp_f32_e32 v145, v91
	v_exp_f32_e32 v128, v92
	v_exp_f32_e32 v129, v93
	v_exp_f32_e32 v130, v94
	v_exp_f32_e32 v132, v95
	v_exp_f32_e32 v133, v96
	v_exp_f32_e32 v136, v97
	v_exp_f32_e32 v137, v98
	v_exp_f32_e32 v147, v99
	v_fmamk_f32 v140, v68, 0x3dd53b94, v138
	v_fmamk_f32 v141, v69, 0x3dd53b94, v138
	v_fmamk_f32 v146, v70, 0x3dd53b94, v138
	v_fmamk_f32 v148, v71, 0x3dd53b94, v138
	v_fmamk_f32 v149, v72, 0x3dd53b94, v138
	v_fmamk_f32 v150, v73, 0x3dd53b94, v138
	v_fmamk_f32 v151, v74, 0x3dd53b94, v138
	v_fmamk_f32 v152, v75, 0x3dd53b94, v138
	v_fmamk_f32 v153, v76, 0x3dd53b94, v138
	v_fmamk_f32 v154, v77, 0x3dd53b94, v138
	v_fmamk_f32 v155, v78, 0x3dd53b94, v138
	v_fmamk_f32 v189, v79, 0x3dd53b94, v138
	v_fmamk_f32 v190, v80, 0x3dd53b94, v138
	v_fmamk_f32 v191, v81, 0x3dd53b94, v138
	v_fmamk_f32 v192, v82, 0x3dd53b94, v138
	v_fmac_f32_e32 v138, 0x3dd53b94, v83
	s_waitcnt lgkmcnt(0)
	s_barrier
	s_nop 1
	ds_read_b128 v[194:197], v181
	ds_read_b128 v[202:205], v181 offset:6144
	ds_read_b128 v[198:201], v182
	ds_read_b128 v[206:209], v182 offset:6144
	v_exp_f32_e32 v193, v140
	v_add_f32_e32 v140, 0, v131
	v_add_f32_e32 v140, v134, v140
	v_add_f32_e32 v140, v135, v140
	v_add_f32_e32 v140, v139, v140
	s_waitcnt lgkmcnt(1)
	v_mfma_scale_f32_32x32x64_f8f6f4 v[84:99], v[194:201], v[116:123], 0, v170, v170 op_sel_hi:[0,0,0]
	s_waitcnt lgkmcnt(0)
	v_mfma_scale_f32_32x32x64_f8f6f4 v[68:83], v[202:209], v[116:123], 0, v170, v170 op_sel_hi:[0,0,0]
	ds_read_b128 v[194:197], v181 offset:64
	ds_read_b128 v[202:205], v181 offset:6208
	ds_read_b128 v[198:201], v182 offset:64
	ds_read_b128 v[206:209], v182 offset:6208
	v_add_f32_e32 v140, v142, v140
	v_add_f32_e32 v140, v143, v140
	v_add_f32_e32 v140, v144, v140
	v_add_f32_e32 v140, v145, v140
	v_add_f32_e32 v140, v128, v140
	s_waitcnt lgkmcnt(1)
	v_mfma_scale_f32_32x32x64_f8f6f4 v[84:99], v[194:201], v[108:115], v[84:99], v170, v170 op_sel_hi:[0,0,0]
	s_waitcnt lgkmcnt(0)
	v_mfma_scale_f32_32x32x64_f8f6f4 v[68:83], v[202:209], v[108:115], v[68:83], v170, v170 op_sel_hi:[0,0,0]
	ds_read_b128 v[194:197], v181 offset:128
	ds_read_b128 v[202:205], v181 offset:6272
	ds_read_b128 v[198:201], v182 offset:128
	ds_read_b128 v[206:209], v182 offset:6272
	v_add_f32_e32 v140, v129, v140
	v_add_f32_e32 v140, v130, v140
	v_add_f32_e32 v140, v132, v140
	v_add_f32_e32 v140, v133, v140
	s_waitcnt lgkmcnt(1)
	v_mfma_scale_f32_32x32x64_f8f6f4 v[84:99], v[194:201], v[100:107], v[84:99], v170, v170 op_sel_hi:[0,0,0]
	v_exp_f32_e32 v194, v141
	v_add_f32_e32 v140, v136, v140
	v_exp_f32_e32 v195, v146
	v_add_f32_e32 v140, v137, v140
	v_exp_f32_e32 v196, v148
	v_add_f32_e32 v140, v147, v140
	v_exp_f32_e32 v197, v149
	v_add_f32_e32 v140, v193, v140
	v_exp_f32_e32 v150, v150
	v_add_f32_e32 v140, v194, v140
	v_exp_f32_e32 v151, v151
	v_add_f32_e32 v140, v195, v140
	v_exp_f32_e32 v152, v152
	v_add_f32_e32 v140, v196, v140
	v_exp_f32_e32 v153, v153
	v_add_f32_e32 v140, v197, v140
	v_exp_f32_e32 v154, v154
	v_add_f32_e32 v140, v150, v140
	v_exp_f32_e32 v155, v155
	v_add_f32_e32 v140, v151, v140
	v_exp_f32_e32 v198, v189
	v_add_f32_e32 v140, v152, v140
	v_exp_f32_e32 v199, v190
	v_add_f32_e32 v140, v153, v140
	v_exp_f32_e32 v191, v191
	v_add_f32_e32 v140, v154, v140
	v_exp_f32_e32 v192, v192
	v_add_f32_e32 v140, v155, v140
	v_exp_f32_e32 v138, v138
	v_add_f32_e32 v140, v198, v140
	v_add_f32_e32 v140, v199, v140
	v_add_f32_e32 v140, v191, v140
	v_add_f32_e32 v140, v192, v140
	v_add_f32_e32 v189, v138, v140
	v_mov_b32_e32 v190, v189
	v_cvt_pk_bf16_f32 v140, v131, v134
	v_cvt_pk_bf16_f32 v141, v135, v139
	v_cvt_pk_bf16_f32 v142, v142, v143
	v_cvt_pk_bf16_f32 v143, v144, v145
	v_cvt_pk_bf16_f32 v144, v128, v129
	v_cvt_pk_bf16_f32 v145, v130, v132
	v_cvt_pk_bf16_f32 v146, v133, v136
	v_cvt_pk_bf16_f32 v147, v137, v147
	v_cvt_pk_bf16_f32 v148, v193, v194
	v_cvt_pk_bf16_f32 v149, v195, v196
	v_cvt_pk_bf16_f32 v150, v197, v150
	v_cvt_pk_bf16_f32 v151, v151, v152
	v_cvt_pk_bf16_f32 v152, v153, v154
	v_cvt_pk_bf16_f32 v153, v155, v198
	v_cvt_pk_bf16_f32 v154, v199, v191
	v_cvt_pk_bf16_f32 v155, v192, v138
	s_waitcnt lgkmcnt(0)
	v_mfma_scale_f32_32x32x64_f8f6f4 v[68:83], v[202:209], v[100:107], v[68:83], v170, v170 op_sel_hi:[0,0,0]
	v_permlane32_swap_b32_e32 v189, v190
	v_permlane32_swap_b32_e32 v140, v142
	v_permlane32_swap_b32_e32 v141, v143
	v_permlane32_swap_b32_e32 v144, v146
	v_permlane32_swap_b32_e32 v145, v147
	v_permlane32_swap_b32_e32 v148, v150
	v_permlane32_swap_b32_e32 v149, v151
	v_permlane32_swap_b32_e32 v152, v154
	v_permlane32_swap_b32_e32 v153, v155
	s_nop 15
	s_nop 15
	s_mov_b32 s0, 0x2a10c000
	v_add_co_u32_e32 v128, vcc, s0, v166
	s_nop 1
	v_addc_co_u32_e32 v129, vcc, 0, v167, vcc
	v_add_co_u32_e32 v132, vcc, 0x2a10e000, v166
	s_nop 1
	v_addc_co_u32_e32 v133, vcc, 0, v167, vcc
	v_add_co_u32_e32 v136, vcc, 0x1e109000, v168
	global_load_dwordx4 v[128:131], v[128:129], off
	s_nop 0
	global_load_dwordx4 v[132:135], v[132:133], off
	v_addc_co_u32_e32 v137, vcc, 0, v169, vcc
	global_load_dwordx4 v[136:139], v[136:137], off
	s_and_saveexec_b64 s[14:15], s[12:13]
	s_cbranch_execz .LBB0_2424
	v_add_co_u32_e32 v124, vcc, 0x1e109000, v164
	s_nop 1
	v_addc_co_u32_e32 v125, vcc, 0, v165, vcc
	global_load_dwordx4 v[124:127], v[124:125], off
